# scan stage-C loads hoisted + vmcnt(0) drain before each GEMM K-loop entry
# speedup vs baseline: 1.0076x; 1.0076x over previous
.LBB0_141:
	s_ashr_i32 s27, s26, 31
	s_lshl_b64 s[8:9], s[26:27], 20
	s_add_u32 s28, s41, s8
	s_addc_u32 s29, s42, s9
	s_and_b64 s[8:9], s[6:7], exec
	s_cselect_b32 s5, s29, s3
	s_cselect_b32 s14, s28, s2
	s_ashr_i32 s25, s24, 31
	s_lshl_b64 s[8:9], s[24:25], 20
	s_add_u32 s30, s23, s8
	s_addc_u32 s31, s40, s9
	s_and_b64 s[8:9], s[6:7], exec
	s_cselect_b32 s25, s31, s1
	s_cselect_b32 s27, s30, s0
	s_add_u32 s8, s2, 0x80080
	s_addc_u32 s9, s3, 0
	s_add_u32 s33, s0, 0x100
	v_mov_b32_e32 v2, 0
	s_addc_u32 s36, s1, 0
	s_mov_b32 s37, -2
	v_mov_b32_e32 v3, v2
	v_mov_b32_e32 v4, v2
	v_mov_b32_e32 v5, v2
	v_mov_b32_e32 v6, v2
	v_mov_b32_e32 v7, v2
	v_mov_b32_e32 v8, v2
	v_mov_b32_e32 v9, v2
	v_mov_b32_e32 v10, v2
	v_mov_b32_e32 v11, v2
	v_mov_b32_e32 v12, v2
	v_mov_b32_e32 v13, v2
	v_mov_b32_e32 v18, v2
	v_mov_b32_e32 v19, v2
	v_mov_b32_e32 v20, v2
	v_mov_b32_e32 v21, v2
	v_mov_b32_e32 v26, v2
	v_mov_b32_e32 v27, v2
	v_mov_b32_e32 v28, v2
	v_mov_b32_e32 v29, v2
	v_mov_b32_e32 v34, v2
	v_mov_b32_e32 v35, v2
	v_mov_b32_e32 v36, v2
	v_mov_b32_e32 v37, v2
	v_mov_b32_e32 v42, v2
	v_mov_b32_e32 v43, v2
	v_mov_b32_e32 v44, v2
	v_mov_b32_e32 v45, v2
	v_mov_b32_e32 v50, v2
	v_mov_b32_e32 v51, v2
	v_mov_b32_e32 v52, v2
	v_mov_b32_e32 v53, v2
	v_mov_b32_e32 v14, v2
	v_mov_b32_e32 v15, v2
	v_mov_b32_e32 v16, v2
	v_mov_b32_e32 v17, v2
	v_mov_b32_e32 v22, v2
	v_mov_b32_e32 v23, v2
	v_mov_b32_e32 v24, v2
	v_mov_b32_e32 v25, v2
	v_mov_b32_e32 v30, v2
	v_mov_b32_e32 v31, v2
	v_mov_b32_e32 v32, v2
	v_mov_b32_e32 v33, v2
	v_mov_b32_e32 v38, v2
	v_mov_b32_e32 v39, v2
	v_mov_b32_e32 v40, v2
	v_mov_b32_e32 v41, v2
	v_mov_b32_e32 v46, v2
	v_mov_b32_e32 v47, v2
	v_mov_b32_e32 v48, v2
	v_mov_b32_e32 v49, v2
	v_mov_b32_e32 v54, v2
	v_mov_b32_e32 v55, v2
	v_mov_b32_e32 v56, v2
	v_mov_b32_e32 v57, v2
	v_mov_b32_e32 v58, v2
	v_mov_b32_e32 v59, v2
	v_mov_b32_e32 v60, v2
	v_mov_b32_e32 v61, v2
	v_mov_b32_e32 v62, v2
	v_mov_b32_e32 v63, v2
	v_mov_b32_e32 v64, v2
	v_mov_b32_e32 v65, v2
	v_mov_b32_e32 v66, v2
	v_mov_b32_e32 v67, v2
	v_mov_b32_e32 v68, v2
	v_mov_b32_e32 v69, v2
	v_mov_b32_e32 v70, v2
	v_mov_b32_e32 v71, v2
	v_mov_b32_e32 v72, v2
	v_mov_b32_e32 v73, v2
	v_mov_b32_e32 v74, v2
	v_mov_b32_e32 v75, v2
	v_mov_b32_e32 v76, v2
	v_mov_b32_e32 v77, v2
	v_mov_b32_e32 v82, v2
	v_mov_b32_e32 v83, v2
	v_mov_b32_e32 v84, v2
	v_mov_b32_e32 v85, v2
	v_mov_b32_e32 v90, v2
	v_mov_b32_e32 v91, v2
	v_mov_b32_e32 v92, v2
	v_mov_b32_e32 v93, v2
	v_mov_b32_e32 v98, v2
	v_mov_b32_e32 v99, v2
	v_mov_b32_e32 v100, v2
	v_mov_b32_e32 v101, v2
	v_mov_b32_e32 v106, v2
	v_mov_b32_e32 v107, v2
	v_mov_b32_e32 v108, v2
	v_mov_b32_e32 v109, v2
	v_mov_b32_e32 v114, v2
	v_mov_b32_e32 v115, v2
	v_mov_b32_e32 v116, v2
	v_mov_b32_e32 v117, v2
	v_mov_b32_e32 v78, v2
	v_mov_b32_e32 v79, v2
	v_mov_b32_e32 v80, v2
	v_mov_b32_e32 v81, v2
	v_mov_b32_e32 v86, v2
	v_mov_b32_e32 v87, v2
	v_mov_b32_e32 v88, v2
	v_mov_b32_e32 v89, v2
	v_mov_b32_e32 v94, v2
	v_mov_b32_e32 v95, v2
	v_mov_b32_e32 v96, v2
	v_mov_b32_e32 v97, v2
	v_mov_b32_e32 v102, v2
	v_mov_b32_e32 v103, v2
	v_mov_b32_e32 v104, v2
	v_mov_b32_e32 v105, v2
	v_mov_b32_e32 v110, v2
	v_mov_b32_e32 v111, v2
	v_mov_b32_e32 v112, v2
	v_mov_b32_e32 v113, v2
	v_mov_b32_e32 v118, v2
	v_mov_b32_e32 v119, v2
	v_mov_b32_e32 v120, v2
	v_mov_b32_e32 v121, v2
	v_mov_b32_e32 v122, v2
	v_mov_b32_e32 v123, v2
	v_mov_b32_e32 v124, v2
	v_mov_b32_e32 v125, v2
	v_mov_b32_e32 v126, v2
	v_mov_b32_e32 v127, v2
	v_mov_b32_e32 v128, v2
	v_mov_b32_e32 v129, v2
	s_waitcnt vmcnt(0)

.LBB0_232:
	s_ashr_i32 s19, s18, 31
	s_lshl_b64 s[0:1], s[18:19], 17
	s_add_u32 s24, s44, s0
	s_addc_u32 s25, s45, s1
	s_and_b64 s[0:1], s[6:7], exec
	s_cselect_b32 s19, s25, s29
	s_cselect_b32 s57, s24, s28
	s_ashr_i32 s17, s16, 31
	s_lshl_b64 s[0:1], s[16:17], 17
	s_add_u32 s26, s33, s0
	s_addc_u32 s27, s42, s1
	s_and_b64 s[0:1], s[6:7], exec
	v_mov_b32_e32 v2, 0
	s_cselect_b32 s17, s27, s23
	s_cselect_b32 s58, s26, s22
	s_mov_b64 s[36:37], 0
	s_mov_b64 s[30:31], -1
	s_mov_b64 s[34:35], 0
	v_mov_b32_e32 v3, v2
	v_mov_b32_e32 v4, v2
	v_mov_b32_e32 v5, v2
	v_mov_b32_e32 v6, v2
	v_mov_b32_e32 v7, v2
	v_mov_b32_e32 v8, v2
	v_mov_b32_e32 v9, v2
	v_mov_b32_e32 v10, v2
	v_mov_b32_e32 v11, v2
	v_mov_b32_e32 v12, v2
	v_mov_b32_e32 v13, v2
	v_mov_b32_e32 v14, v2
	v_mov_b32_e32 v15, v2
	v_mov_b32_e32 v16, v2
	v_mov_b32_e32 v17, v2
	v_mov_b32_e32 v26, v2
	v_mov_b32_e32 v27, v2
	v_mov_b32_e32 v28, v2
	v_mov_b32_e32 v29, v2
	v_mov_b32_e32 v30, v2
	v_mov_b32_e32 v31, v2
	v_mov_b32_e32 v32, v2
	v_mov_b32_e32 v33, v2
	v_mov_b32_e32 v42, v2
	v_mov_b32_e32 v43, v2
	v_mov_b32_e32 v44, v2
	v_mov_b32_e32 v45, v2
	v_mov_b32_e32 v46, v2
	v_mov_b32_e32 v47, v2
	v_mov_b32_e32 v48, v2
	v_mov_b32_e32 v49, v2
	v_mov_b32_e32 v18, v2
	v_mov_b32_e32 v19, v2
	v_mov_b32_e32 v20, v2
	v_mov_b32_e32 v21, v2
	v_mov_b32_e32 v22, v2
	v_mov_b32_e32 v23, v2
	v_mov_b32_e32 v24, v2
	v_mov_b32_e32 v25, v2
	v_mov_b32_e32 v34, v2
	v_mov_b32_e32 v35, v2
	v_mov_b32_e32 v36, v2
	v_mov_b32_e32 v37, v2
	v_mov_b32_e32 v38, v2
	v_mov_b32_e32 v39, v2
	v_mov_b32_e32 v40, v2
	v_mov_b32_e32 v41, v2
	v_mov_b32_e32 v50, v2
	v_mov_b32_e32 v51, v2
	v_mov_b32_e32 v52, v2
	v_mov_b32_e32 v53, v2
	v_mov_b32_e32 v54, v2
	v_mov_b32_e32 v55, v2
	v_mov_b32_e32 v56, v2
	v_mov_b32_e32 v57, v2
	v_mov_b32_e32 v58, v2
	v_mov_b32_e32 v59, v2
	v_mov_b32_e32 v60, v2
	v_mov_b32_e32 v61, v2
	v_mov_b32_e32 v62, v2
	v_mov_b32_e32 v63, v2
	v_mov_b32_e32 v64, v2
	v_mov_b32_e32 v65, v2
	v_mov_b32_e32 v66, v2
	v_mov_b32_e32 v67, v2
	v_mov_b32_e32 v68, v2
	v_mov_b32_e32 v69, v2
	v_mov_b32_e32 v70, v2
	v_mov_b32_e32 v71, v2
	v_mov_b32_e32 v72, v2
	v_mov_b32_e32 v73, v2
	v_mov_b32_e32 v74, v2
	v_mov_b32_e32 v75, v2
	v_mov_b32_e32 v76, v2
	v_mov_b32_e32 v77, v2
	v_mov_b32_e32 v78, v2
	v_mov_b32_e32 v79, v2
	v_mov_b32_e32 v80, v2
	v_mov_b32_e32 v81, v2
	v_mov_b32_e32 v90, v2
	v_mov_b32_e32 v91, v2
	v_mov_b32_e32 v92, v2
	v_mov_b32_e32 v93, v2
	v_mov_b32_e32 v94, v2
	v_mov_b32_e32 v95, v2
	v_mov_b32_e32 v96, v2
	v_mov_b32_e32 v97, v2
	v_mov_b32_e32 v106, v2
	v_mov_b32_e32 v107, v2
	v_mov_b32_e32 v108, v2
	v_mov_b32_e32 v109, v2
	v_mov_b32_e32 v110, v2
	v_mov_b32_e32 v111, v2
	v_mov_b32_e32 v112, v2
	v_mov_b32_e32 v113, v2
	v_mov_b32_e32 v82, v2
	v_mov_b32_e32 v83, v2
	v_mov_b32_e32 v84, v2
	v_mov_b32_e32 v85, v2
	v_mov_b32_e32 v86, v2
	v_mov_b32_e32 v87, v2
	v_mov_b32_e32 v88, v2
	v_mov_b32_e32 v89, v2
	v_mov_b32_e32 v98, v2
	v_mov_b32_e32 v99, v2
	v_mov_b32_e32 v100, v2
	v_mov_b32_e32 v101, v2
	v_mov_b32_e32 v102, v2
	v_mov_b32_e32 v103, v2
	v_mov_b32_e32 v104, v2
	v_mov_b32_e32 v105, v2
	v_mov_b32_e32 v114, v2
	v_mov_b32_e32 v115, v2
	v_mov_b32_e32 v116, v2
	v_mov_b32_e32 v117, v2
	v_mov_b32_e32 v118, v2
	v_mov_b32_e32 v119, v2
	v_mov_b32_e32 v120, v2
	v_mov_b32_e32 v121, v2
	v_mov_b32_e32 v122, v2
	v_mov_b32_e32 v123, v2
	v_mov_b32_e32 v124, v2
	v_mov_b32_e32 v125, v2
	v_mov_b32_e32 v126, v2
	v_mov_b32_e32 v127, v2
	v_mov_b32_e32 v128, v2
	v_mov_b32_e32 v129, v2
	s_waitcnt vmcnt(0)

.LBB0_654:
	s_ashr_i32 s23, s22, 31
	s_lshl_b64 s[24:25], s[22:23], 20
	s_add_u32 s24, s36, s24
	s_addc_u32 s25, s37, s25
	s_and_b64 s[26:27], s[6:7], exec
	s_cselect_b32 s23, s25, s3
	s_cselect_b32 s49, s24, s2
	s_ashr_i32 s21, s20, 31
	s_lshl_b64 s[26:27], s[20:21], 20
	s_add_u32 s26, s33, s26
	s_addc_u32 s27, s34, s27
	s_and_b64 s[30:31], s[6:7], exec
	s_cselect_b32 s21, s27, s1
	s_cselect_b32 s50, s26, s0
	s_add_u32 s30, s2, 0x80080
	s_addc_u32 s31, s3, 0
	s_add_u32 s51, s0, 0x100
	v_mov_b32_e32 v2, 0
	s_addc_u32 s52, s1, 0
	s_mov_b32 s53, -2
	v_mov_b32_e32 v3, v2
	v_mov_b32_e32 v4, v2
	v_mov_b32_e32 v5, v2
	v_mov_b32_e32 v6, v2
	v_mov_b32_e32 v7, v2
	v_mov_b32_e32 v8, v2
	v_mov_b32_e32 v9, v2
	v_mov_b32_e32 v18, v2
	v_mov_b32_e32 v19, v2
	v_mov_b32_e32 v20, v2
	v_mov_b32_e32 v21, v2
	v_mov_b32_e32 v22, v2
	v_mov_b32_e32 v23, v2
	v_mov_b32_e32 v24, v2
	v_mov_b32_e32 v25, v2
	v_mov_b32_e32 v34, v2
	v_mov_b32_e32 v35, v2
	v_mov_b32_e32 v36, v2
	v_mov_b32_e32 v37, v2
	v_mov_b32_e32 v38, v2
	v_mov_b32_e32 v39, v2
	v_mov_b32_e32 v40, v2
	v_mov_b32_e32 v41, v2
	v_mov_b32_e32 v50, v2
	v_mov_b32_e32 v51, v2
	v_mov_b32_e32 v52, v2
	v_mov_b32_e32 v53, v2
	v_mov_b32_e32 v54, v2
	v_mov_b32_e32 v55, v2
	v_mov_b32_e32 v56, v2
	v_mov_b32_e32 v57, v2
	v_mov_b32_e32 v10, v2
	v_mov_b32_e32 v11, v2
	v_mov_b32_e32 v12, v2
	v_mov_b32_e32 v13, v2
	v_mov_b32_e32 v14, v2
	v_mov_b32_e32 v15, v2
	v_mov_b32_e32 v16, v2
	v_mov_b32_e32 v17, v2
	v_mov_b32_e32 v26, v2
	v_mov_b32_e32 v27, v2
	v_mov_b32_e32 v28, v2
	v_mov_b32_e32 v29, v2
	v_mov_b32_e32 v30, v2
	v_mov_b32_e32 v31, v2
	v_mov_b32_e32 v32, v2
	v_mov_b32_e32 v33, v2
	v_mov_b32_e32 v42, v2
	v_mov_b32_e32 v43, v2
	v_mov_b32_e32 v44, v2
	v_mov_b32_e32 v45, v2
	v_mov_b32_e32 v46, v2
	v_mov_b32_e32 v47, v2
	v_mov_b32_e32 v48, v2
	v_mov_b32_e32 v49, v2
	v_mov_b32_e32 v58, v2
	v_mov_b32_e32 v59, v2
	v_mov_b32_e32 v60, v2
	v_mov_b32_e32 v61, v2
	v_mov_b32_e32 v62, v2
	v_mov_b32_e32 v63, v2
	v_mov_b32_e32 v64, v2
	v_mov_b32_e32 v65, v2
	v_mov_b32_e32 v66, v2
	v_mov_b32_e32 v67, v2
	v_mov_b32_e32 v68, v2
	v_mov_b32_e32 v69, v2
	v_mov_b32_e32 v70, v2
	v_mov_b32_e32 v71, v2
	v_mov_b32_e32 v72, v2
	v_mov_b32_e32 v73, v2
	v_mov_b32_e32 v82, v2
	v_mov_b32_e32 v83, v2
	v_mov_b32_e32 v84, v2
	v_mov_b32_e32 v85, v2
	v_mov_b32_e32 v86, v2
	v_mov_b32_e32 v87, v2
	v_mov_b32_e32 v88, v2
	v_mov_b32_e32 v89, v2
	v_mov_b32_e32 v98, v2
	v_mov_b32_e32 v99, v2
	v_mov_b32_e32 v100, v2
	v_mov_b32_e32 v101, v2
	v_mov_b32_e32 v102, v2
	v_mov_b32_e32 v103, v2
	v_mov_b32_e32 v104, v2
	v_mov_b32_e32 v105, v2
	v_mov_b32_e32 v114, v2
	v_mov_b32_e32 v115, v2
	v_mov_b32_e32 v116, v2
	v_mov_b32_e32 v117, v2
	v_mov_b32_e32 v118, v2
	v_mov_b32_e32 v119, v2
	v_mov_b32_e32 v120, v2
	v_mov_b32_e32 v121, v2
	v_mov_b32_e32 v74, v2
	v_mov_b32_e32 v75, v2
	v_mov_b32_e32 v76, v2
	v_mov_b32_e32 v77, v2
	v_mov_b32_e32 v78, v2
	v_mov_b32_e32 v79, v2
	v_mov_b32_e32 v80, v2
	v_mov_b32_e32 v81, v2
	v_mov_b32_e32 v90, v2
	v_mov_b32_e32 v91, v2
	v_mov_b32_e32 v92, v2
	v_mov_b32_e32 v93, v2
	v_mov_b32_e32 v94, v2
	v_mov_b32_e32 v95, v2
	v_mov_b32_e32 v96, v2
	v_mov_b32_e32 v97, v2
	v_mov_b32_e32 v106, v2
	v_mov_b32_e32 v107, v2
	v_mov_b32_e32 v108, v2
	v_mov_b32_e32 v109, v2
	v_mov_b32_e32 v110, v2
	v_mov_b32_e32 v111, v2
	v_mov_b32_e32 v112, v2
	v_mov_b32_e32 v113, v2
	v_mov_b32_e32 v122, v2
	v_mov_b32_e32 v123, v2
	v_mov_b32_e32 v124, v2
	v_mov_b32_e32 v125, v2
	v_mov_b32_e32 v126, v2
	v_mov_b32_e32 v127, v2
	v_mov_b32_e32 v128, v2
	v_mov_b32_e32 v129, v2
	s_waitcnt vmcnt(0)

.LBB0_739:
	s_ashr_i32 s25, s24, 31
	s_lshl_b64 s[26:27], s[24:25], 20
	s_add_u32 s26, s10, s26
	s_addc_u32 s27, s11, s27
	s_and_b64 s[28:29], s[6:7], exec
	s_cselect_b32 s25, s27, s3
	s_cselect_b32 s47, s26, s2
	s_ashr_i32 s23, s22, 31
	s_lshl_b64 s[28:29], s[22:23], 20
	s_add_u32 s28, s34, s28
	s_addc_u32 s29, s35, s29
	s_and_b64 s[30:31], s[6:7], exec
	s_cselect_b32 s23, s29, s1
	s_cselect_b32 s48, s28, s0
	s_add_u32 s30, s2, 0x80080
	s_addc_u32 s31, s3, 0
	s_add_u32 s49, s0, 0x100
	v_mov_b32_e32 v2, 0
	s_addc_u32 s50, s1, 0
	s_mov_b32 s51, -2
	v_mov_b32_e32 v3, v2
	v_mov_b32_e32 v4, v2
	v_mov_b32_e32 v5, v2
	v_mov_b32_e32 v6, v2
	v_mov_b32_e32 v7, v2
	v_mov_b32_e32 v8, v2
	v_mov_b32_e32 v9, v2
	v_mov_b32_e32 v18, v2
	v_mov_b32_e32 v19, v2
	v_mov_b32_e32 v20, v2
	v_mov_b32_e32 v21, v2
	v_mov_b32_e32 v22, v2
	v_mov_b32_e32 v23, v2
	v_mov_b32_e32 v24, v2
	v_mov_b32_e32 v25, v2
	v_mov_b32_e32 v34, v2
	v_mov_b32_e32 v35, v2
	v_mov_b32_e32 v36, v2
	v_mov_b32_e32 v37, v2
	v_mov_b32_e32 v38, v2
	v_mov_b32_e32 v39, v2
	v_mov_b32_e32 v40, v2
	v_mov_b32_e32 v41, v2
	v_mov_b32_e32 v50, v2
	v_mov_b32_e32 v51, v2
	v_mov_b32_e32 v52, v2
	v_mov_b32_e32 v53, v2
	v_mov_b32_e32 v54, v2
	v_mov_b32_e32 v55, v2
	v_mov_b32_e32 v56, v2
	v_mov_b32_e32 v57, v2
	v_mov_b32_e32 v10, v2
	v_mov_b32_e32 v11, v2
	v_mov_b32_e32 v12, v2
	v_mov_b32_e32 v13, v2
	v_mov_b32_e32 v14, v2
	v_mov_b32_e32 v15, v2
	v_mov_b32_e32 v16, v2
	v_mov_b32_e32 v17, v2
	v_mov_b32_e32 v26, v2
	v_mov_b32_e32 v27, v2
	v_mov_b32_e32 v28, v2
	v_mov_b32_e32 v29, v2
	v_mov_b32_e32 v30, v2
	v_mov_b32_e32 v31, v2
	v_mov_b32_e32 v32, v2
	v_mov_b32_e32 v33, v2
	v_mov_b32_e32 v42, v2
	v_mov_b32_e32 v43, v2
	v_mov_b32_e32 v44, v2
	v_mov_b32_e32 v45, v2
	v_mov_b32_e32 v46, v2
	v_mov_b32_e32 v47, v2
	v_mov_b32_e32 v48, v2
	v_mov_b32_e32 v49, v2
	v_mov_b32_e32 v58, v2
	v_mov_b32_e32 v59, v2
	v_mov_b32_e32 v60, v2
	v_mov_b32_e32 v61, v2
	v_mov_b32_e32 v62, v2
	v_mov_b32_e32 v63, v2
	v_mov_b32_e32 v64, v2
	v_mov_b32_e32 v65, v2
	v_mov_b32_e32 v66, v2
	v_mov_b32_e32 v67, v2
	v_mov_b32_e32 v68, v2
	v_mov_b32_e32 v69, v2
	v_mov_b32_e32 v70, v2
	v_mov_b32_e32 v71, v2
	v_mov_b32_e32 v72, v2
	v_mov_b32_e32 v73, v2
	v_mov_b32_e32 v82, v2
	v_mov_b32_e32 v83, v2
	v_mov_b32_e32 v84, v2
	v_mov_b32_e32 v85, v2
	v_mov_b32_e32 v86, v2
	v_mov_b32_e32 v87, v2
	v_mov_b32_e32 v88, v2
	v_mov_b32_e32 v89, v2
	v_mov_b32_e32 v98, v2
	v_mov_b32_e32 v99, v2
	v_mov_b32_e32 v100, v2
	v_mov_b32_e32 v101, v2
	v_mov_b32_e32 v102, v2
	v_mov_b32_e32 v103, v2
	v_mov_b32_e32 v104, v2
	v_mov_b32_e32 v105, v2
	v_mov_b32_e32 v114, v2
	v_mov_b32_e32 v115, v2
	v_mov_b32_e32 v116, v2
	v_mov_b32_e32 v117, v2
	v_mov_b32_e32 v118, v2
	v_mov_b32_e32 v119, v2
	v_mov_b32_e32 v120, v2
	v_mov_b32_e32 v121, v2
	v_mov_b32_e32 v74, v2
	v_mov_b32_e32 v75, v2
	v_mov_b32_e32 v76, v2
	v_mov_b32_e32 v77, v2
	v_mov_b32_e32 v78, v2
	v_mov_b32_e32 v79, v2
	v_mov_b32_e32 v80, v2
	v_mov_b32_e32 v81, v2
	v_mov_b32_e32 v90, v2
	v_mov_b32_e32 v91, v2
	v_mov_b32_e32 v92, v2
	v_mov_b32_e32 v93, v2
	v_mov_b32_e32 v94, v2
	v_mov_b32_e32 v95, v2
	v_mov_b32_e32 v96, v2
	v_mov_b32_e32 v97, v2
	v_mov_b32_e32 v106, v2
	v_mov_b32_e32 v107, v2
	v_mov_b32_e32 v108, v2
	v_mov_b32_e32 v109, v2
	v_mov_b32_e32 v110, v2
	v_mov_b32_e32 v111, v2
	v_mov_b32_e32 v112, v2
	v_mov_b32_e32 v113, v2
	v_mov_b32_e32 v122, v2
	v_mov_b32_e32 v123, v2
	v_mov_b32_e32 v124, v2
	v_mov_b32_e32 v125, v2
	v_mov_b32_e32 v126, v2
	v_mov_b32_e32 v127, v2
	v_mov_b32_e32 v128, v2
	v_mov_b32_e32 v129, v2
	s_waitcnt vmcnt(0)

.LBB0_924:
	s_add_u32 s4, s4, 0x80080
	s_addc_u32 s5, s5, 0
	s_add_u32 s14, s26, 0x100
	v_mov_b32_e32 v2, 0
	s_addc_u32 s23, s27, 0
	s_mov_b32 s26, -2
	v_mov_b32_e32 v3, v2
	v_mov_b32_e32 v4, v2
	v_mov_b32_e32 v5, v2
	v_mov_b32_e32 v6, v2
	v_mov_b32_e32 v7, v2
	v_mov_b32_e32 v8, v2
	v_mov_b32_e32 v9, v2
	v_mov_b32_e32 v10, v2
	v_mov_b32_e32 v11, v2
	v_mov_b32_e32 v12, v2
	v_mov_b32_e32 v13, v2
	v_mov_b32_e32 v14, v2
	v_mov_b32_e32 v15, v2
	v_mov_b32_e32 v16, v2
	v_mov_b32_e32 v17, v2
	v_mov_b32_e32 v26, v2
	v_mov_b32_e32 v27, v2
	v_mov_b32_e32 v28, v2
	v_mov_b32_e32 v29, v2
	v_mov_b32_e32 v30, v2
	v_mov_b32_e32 v31, v2
	v_mov_b32_e32 v32, v2
	v_mov_b32_e32 v33, v2
	v_mov_b32_e32 v42, v2
	v_mov_b32_e32 v43, v2
	v_mov_b32_e32 v44, v2
	v_mov_b32_e32 v45, v2
	v_mov_b32_e32 v46, v2
	v_mov_b32_e32 v47, v2
	v_mov_b32_e32 v48, v2
	v_mov_b32_e32 v49, v2
	v_mov_b32_e32 v18, v2
	v_mov_b32_e32 v19, v2
	v_mov_b32_e32 v20, v2
	v_mov_b32_e32 v21, v2
	v_mov_b32_e32 v22, v2
	v_mov_b32_e32 v23, v2
	v_mov_b32_e32 v24, v2
	v_mov_b32_e32 v25, v2
	v_mov_b32_e32 v34, v2
	v_mov_b32_e32 v35, v2
	v_mov_b32_e32 v36, v2
	v_mov_b32_e32 v37, v2
	v_mov_b32_e32 v38, v2
	v_mov_b32_e32 v39, v2
	v_mov_b32_e32 v40, v2
	v_mov_b32_e32 v41, v2
	v_mov_b32_e32 v50, v2
	v_mov_b32_e32 v51, v2
	v_mov_b32_e32 v52, v2
	v_mov_b32_e32 v53, v2
	v_mov_b32_e32 v54, v2
	v_mov_b32_e32 v55, v2
	v_mov_b32_e32 v56, v2
	v_mov_b32_e32 v57, v2
	v_mov_b32_e32 v58, v2
	v_mov_b32_e32 v59, v2
	v_mov_b32_e32 v60, v2
	v_mov_b32_e32 v61, v2
	v_mov_b32_e32 v62, v2
	v_mov_b32_e32 v63, v2
	v_mov_b32_e32 v64, v2
	v_mov_b32_e32 v65, v2
	v_mov_b32_e32 v66, v2
	v_mov_b32_e32 v67, v2
	v_mov_b32_e32 v68, v2
	v_mov_b32_e32 v69, v2
	v_mov_b32_e32 v70, v2
	v_mov_b32_e32 v71, v2
	v_mov_b32_e32 v72, v2
	v_mov_b32_e32 v73, v2
	v_mov_b32_e32 v74, v2
	v_mov_b32_e32 v75, v2
	v_mov_b32_e32 v76, v2
	v_mov_b32_e32 v77, v2
	v_mov_b32_e32 v78, v2
	v_mov_b32_e32 v79, v2
	v_mov_b32_e32 v80, v2
	v_mov_b32_e32 v81, v2
	v_mov_b32_e32 v90, v2
	v_mov_b32_e32 v91, v2
	v_mov_b32_e32 v92, v2
	v_mov_b32_e32 v93, v2
	v_mov_b32_e32 v94, v2
	v_mov_b32_e32 v95, v2
	v_mov_b32_e32 v96, v2
	v_mov_b32_e32 v97, v2
	v_mov_b32_e32 v106, v2
	v_mov_b32_e32 v107, v2
	v_mov_b32_e32 v108, v2
	v_mov_b32_e32 v109, v2
	v_mov_b32_e32 v110, v2
	v_mov_b32_e32 v111, v2
	v_mov_b32_e32 v112, v2
	v_mov_b32_e32 v113, v2
	v_mov_b32_e32 v82, v2
	v_mov_b32_e32 v83, v2
	v_mov_b32_e32 v84, v2
	v_mov_b32_e32 v85, v2
	v_mov_b32_e32 v86, v2
	v_mov_b32_e32 v87, v2
	v_mov_b32_e32 v88, v2
	v_mov_b32_e32 v89, v2
	v_mov_b32_e32 v98, v2
	v_mov_b32_e32 v99, v2
	v_mov_b32_e32 v100, v2
	v_mov_b32_e32 v101, v2
	v_mov_b32_e32 v102, v2
	v_mov_b32_e32 v103, v2
	v_mov_b32_e32 v104, v2
	v_mov_b32_e32 v105, v2
	v_mov_b32_e32 v114, v2
	v_mov_b32_e32 v115, v2
	v_mov_b32_e32 v116, v2
	v_mov_b32_e32 v117, v2
	v_mov_b32_e32 v118, v2
	v_mov_b32_e32 v119, v2
	v_mov_b32_e32 v120, v2
	v_mov_b32_e32 v121, v2
	v_mov_b32_e32 v122, v2
	v_mov_b32_e32 v123, v2
	v_mov_b32_e32 v124, v2
	v_mov_b32_e32 v125, v2
	v_mov_b32_e32 v126, v2
	v_mov_b32_e32 v127, v2
	v_mov_b32_e32 v128, v2
	v_mov_b32_e32 v129, v2
	s_waitcnt vmcnt(0)

.LBB0_986:
	s_ashr_i32 s19, s18, 31
	s_lshl_b64 s[0:1], s[18:19], 17
	s_add_u32 s22, s45, s0
	s_addc_u32 s23, s46, s1
	s_and_b64 s[0:1], s[6:7], exec
	s_cselect_b32 s19, s23, s29
	s_cselect_b32 s60, s22, s28
	s_ashr_i32 s21, s20, 31
	s_lshl_b64 s[0:1], s[20:21], 17
	s_add_u32 s24, s42, s0
	s_addc_u32 s25, s43, s1
	s_and_b64 s[0:1], s[6:7], exec
	v_mov_b32_e32 v2, 0
	s_cselect_b32 s21, s25, s27
	s_cselect_b32 s61, s24, s26
	s_mov_b64 s[36:37], 0
	s_mov_b64 s[30:31], -1
	s_mov_b64 s[34:35], 0
	v_mov_b32_e32 v3, v2
	v_mov_b32_e32 v4, v2
	v_mov_b32_e32 v5, v2
	v_mov_b32_e32 v6, v2
	v_mov_b32_e32 v7, v2
	v_mov_b32_e32 v8, v2
	v_mov_b32_e32 v9, v2
	v_mov_b32_e32 v10, v2
	v_mov_b32_e32 v11, v2
	v_mov_b32_e32 v12, v2
	v_mov_b32_e32 v13, v2
	v_mov_b32_e32 v14, v2
	v_mov_b32_e32 v15, v2
	v_mov_b32_e32 v16, v2
	v_mov_b32_e32 v17, v2
	v_mov_b32_e32 v26, v2
	v_mov_b32_e32 v27, v2
	v_mov_b32_e32 v28, v2
	v_mov_b32_e32 v29, v2
	v_mov_b32_e32 v30, v2
	v_mov_b32_e32 v31, v2
	v_mov_b32_e32 v32, v2
	v_mov_b32_e32 v33, v2
	v_mov_b32_e32 v42, v2
	v_mov_b32_e32 v43, v2
	v_mov_b32_e32 v44, v2
	v_mov_b32_e32 v45, v2
	v_mov_b32_e32 v46, v2
	v_mov_b32_e32 v47, v2
	v_mov_b32_e32 v48, v2
	v_mov_b32_e32 v49, v2
	v_mov_b32_e32 v18, v2
	v_mov_b32_e32 v19, v2
	v_mov_b32_e32 v20, v2
	v_mov_b32_e32 v21, v2
	v_mov_b32_e32 v22, v2
	v_mov_b32_e32 v23, v2
	v_mov_b32_e32 v24, v2
	v_mov_b32_e32 v25, v2
	v_mov_b32_e32 v34, v2
	v_mov_b32_e32 v35, v2
	v_mov_b32_e32 v36, v2
	v_mov_b32_e32 v37, v2
	v_mov_b32_e32 v38, v2
	v_mov_b32_e32 v39, v2
	v_mov_b32_e32 v40, v2
	v_mov_b32_e32 v41, v2
	v_mov_b32_e32 v50, v2
	v_mov_b32_e32 v51, v2
	v_mov_b32_e32 v52, v2
	v_mov_b32_e32 v53, v2
	v_mov_b32_e32 v54, v2
	v_mov_b32_e32 v55, v2
	v_mov_b32_e32 v56, v2
	v_mov_b32_e32 v57, v2
	v_mov_b32_e32 v58, v2
	v_mov_b32_e32 v59, v2
	v_mov_b32_e32 v60, v2
	v_mov_b32_e32 v61, v2
	v_mov_b32_e32 v62, v2
	v_mov_b32_e32 v63, v2
	v_mov_b32_e32 v64, v2
	v_mov_b32_e32 v65, v2
	v_mov_b32_e32 v66, v2
	v_mov_b32_e32 v67, v2
	v_mov_b32_e32 v68, v2
	v_mov_b32_e32 v69, v2
	v_mov_b32_e32 v70, v2
	v_mov_b32_e32 v71, v2
	v_mov_b32_e32 v72, v2
	v_mov_b32_e32 v73, v2
	v_mov_b32_e32 v74, v2
	v_mov_b32_e32 v75, v2
	v_mov_b32_e32 v76, v2
	v_mov_b32_e32 v77, v2
	v_mov_b32_e32 v78, v2
	v_mov_b32_e32 v79, v2
	v_mov_b32_e32 v80, v2
	v_mov_b32_e32 v81, v2
	v_mov_b32_e32 v90, v2
	v_mov_b32_e32 v91, v2
	v_mov_b32_e32 v92, v2
	v_mov_b32_e32 v93, v2
	v_mov_b32_e32 v94, v2
	v_mov_b32_e32 v95, v2
	v_mov_b32_e32 v96, v2
	v_mov_b32_e32 v97, v2
	v_mov_b32_e32 v106, v2
	v_mov_b32_e32 v107, v2
	v_mov_b32_e32 v108, v2
	v_mov_b32_e32 v109, v2
	v_mov_b32_e32 v110, v2
	v_mov_b32_e32 v111, v2
	v_mov_b32_e32 v112, v2
	v_mov_b32_e32 v113, v2
	v_mov_b32_e32 v82, v2
	v_mov_b32_e32 v83, v2
	v_mov_b32_e32 v84, v2
	v_mov_b32_e32 v85, v2
	v_mov_b32_e32 v86, v2
	v_mov_b32_e32 v87, v2
	v_mov_b32_e32 v88, v2
	v_mov_b32_e32 v89, v2
	v_mov_b32_e32 v98, v2
	v_mov_b32_e32 v99, v2
	v_mov_b32_e32 v100, v2
	v_mov_b32_e32 v101, v2
	v_mov_b32_e32 v102, v2
	v_mov_b32_e32 v103, v2
	v_mov_b32_e32 v104, v2
	v_mov_b32_e32 v105, v2
	v_mov_b32_e32 v114, v2
	v_mov_b32_e32 v115, v2
	v_mov_b32_e32 v116, v2
	v_mov_b32_e32 v117, v2
	v_mov_b32_e32 v118, v2
	v_mov_b32_e32 v119, v2
	v_mov_b32_e32 v120, v2
	v_mov_b32_e32 v121, v2
	v_mov_b32_e32 v122, v2
	v_mov_b32_e32 v123, v2
	v_mov_b32_e32 v124, v2
	v_mov_b32_e32 v125, v2
	v_mov_b32_e32 v126, v2
	v_mov_b32_e32 v127, v2
	v_mov_b32_e32 v128, v2
	v_mov_b32_e32 v129, v2
	s_waitcnt vmcnt(0)

.LBB0_1078:
	s_ashr_i32 s25, s24, 31
	s_lshl_b64 s[0:1], s[24:25], 17
	s_cmp_gt_i32 s22, 7
	s_cselect_b32 s2, 0x100, 0
	s_add_u32 s0, s38, s0
	s_addc_u32 s1, s39, s1
	s_add_u32 s26, s0, s2
	s_addc_u32 s27, s1, 0
	s_ashr_i32 s23, s22, 31
	s_lshl_b64 s[0:1], s[22:23], 17
	s_add_u32 s0, s33, s0
	s_addc_u32 s1, s36, s1
	s_add_u32 s28, s0, s2
	v_mov_b32_e32 v125, 0
	s_addc_u32 s29, s1, 0
	s_andn2_b64 vcc, exec, s[18:19]
	v_mov_b32_e32 v124, v125
	v_mov_b32_e32 v123, v125
	v_mov_b32_e32 v122, v125
	v_mov_b32_e32 v129, v125
	v_mov_b32_e32 v128, v125
	v_mov_b32_e32 v127, v125
	v_mov_b32_e32 v126, v125
	v_mov_b32_e32 v113, v125
	v_mov_b32_e32 v112, v125
	v_mov_b32_e32 v111, v125
	v_mov_b32_e32 v110, v125
	v_mov_b32_e32 v109, v125
	v_mov_b32_e32 v108, v125
	v_mov_b32_e32 v107, v125
	v_mov_b32_e32 v106, v125
	v_mov_b32_e32 v97, v125
	v_mov_b32_e32 v96, v125
	v_mov_b32_e32 v95, v125
	v_mov_b32_e32 v94, v125
	v_mov_b32_e32 v93, v125
	v_mov_b32_e32 v92, v125
	v_mov_b32_e32 v91, v125
	v_mov_b32_e32 v90, v125
	v_mov_b32_e32 v81, v125
	v_mov_b32_e32 v80, v125
	v_mov_b32_e32 v79, v125
	v_mov_b32_e32 v78, v125
	v_mov_b32_e32 v77, v125
	v_mov_b32_e32 v76, v125
	v_mov_b32_e32 v75, v125
	v_mov_b32_e32 v74, v125
	v_mov_b32_e32 v121, v125
	v_mov_b32_e32 v120, v125
	v_mov_b32_e32 v119, v125
	v_mov_b32_e32 v118, v125
	v_mov_b32_e32 v117, v125
	v_mov_b32_e32 v116, v125
	v_mov_b32_e32 v115, v125
	v_mov_b32_e32 v114, v125
	v_mov_b32_e32 v105, v125
	v_mov_b32_e32 v104, v125
	v_mov_b32_e32 v103, v125
	v_mov_b32_e32 v102, v125
	v_mov_b32_e32 v101, v125
	v_mov_b32_e32 v100, v125
	v_mov_b32_e32 v99, v125
	v_mov_b32_e32 v98, v125
	v_mov_b32_e32 v89, v125
	v_mov_b32_e32 v88, v125
	v_mov_b32_e32 v87, v125
	v_mov_b32_e32 v86, v125
	v_mov_b32_e32 v85, v125
	v_mov_b32_e32 v84, v125
	v_mov_b32_e32 v83, v125
	v_mov_b32_e32 v82, v125
	v_mov_b32_e32 v73, v125
	v_mov_b32_e32 v72, v125
	v_mov_b32_e32 v71, v125
	v_mov_b32_e32 v70, v125
	v_mov_b32_e32 v69, v125
	v_mov_b32_e32 v68, v125
	v_mov_b32_e32 v67, v125
	v_mov_b32_e32 v66, v125
	v_mov_b32_e32 v65, v125
	v_mov_b32_e32 v64, v125
	v_mov_b32_e32 v63, v125
	v_mov_b32_e32 v62, v125
	v_mov_b32_e32 v61, v125
	v_mov_b32_e32 v60, v125
	v_mov_b32_e32 v59, v125
	v_mov_b32_e32 v58, v125
	v_mov_b32_e32 v49, v125
	v_mov_b32_e32 v48, v125
	v_mov_b32_e32 v47, v125
	v_mov_b32_e32 v46, v125
	v_mov_b32_e32 v45, v125
	v_mov_b32_e32 v44, v125
	v_mov_b32_e32 v43, v125
	v_mov_b32_e32 v42, v125
	v_mov_b32_e32 v33, v125
	v_mov_b32_e32 v32, v125
	v_mov_b32_e32 v31, v125
	v_mov_b32_e32 v30, v125
	v_mov_b32_e32 v29, v125
	v_mov_b32_e32 v28, v125
	v_mov_b32_e32 v27, v125
	v_mov_b32_e32 v26, v125
	v_mov_b32_e32 v17, v125
	v_mov_b32_e32 v16, v125
	v_mov_b32_e32 v15, v125
	v_mov_b32_e32 v14, v125
	v_mov_b32_e32 v13, v125
	v_mov_b32_e32 v12, v125
	v_mov_b32_e32 v11, v125
	v_mov_b32_e32 v10, v125
	v_mov_b32_e32 v57, v125
	v_mov_b32_e32 v56, v125
	v_mov_b32_e32 v55, v125
	v_mov_b32_e32 v54, v125
	v_mov_b32_e32 v53, v125
	v_mov_b32_e32 v52, v125
	v_mov_b32_e32 v51, v125
	v_mov_b32_e32 v50, v125
	v_mov_b32_e32 v41, v125
	v_mov_b32_e32 v40, v125
	v_mov_b32_e32 v39, v125
	v_mov_b32_e32 v38, v125
	v_mov_b32_e32 v37, v125
	v_mov_b32_e32 v36, v125
	v_mov_b32_e32 v35, v125
	v_mov_b32_e32 v34, v125
	v_mov_b32_e32 v25, v125
	v_mov_b32_e32 v24, v125
	v_mov_b32_e32 v23, v125
	v_mov_b32_e32 v22, v125
	v_mov_b32_e32 v21, v125
	v_mov_b32_e32 v20, v125
	v_mov_b32_e32 v19, v125
	v_mov_b32_e32 v18, v125
	v_mov_b32_e32 v9, v125
	v_mov_b32_e32 v8, v125
	v_mov_b32_e32 v7, v125
	v_mov_b32_e32 v6, v125
	v_mov_b32_e32 v5, v125
	v_mov_b32_e32 v4, v125
	v_mov_b32_e32 v3, v125
	v_mov_b32_e32 v2, v125
	s_cbranch_vccnz .LBB0_1081
	s_and_b64 s[0:1], s[6:7], exec
	s_cselect_b32 s23, s27, s31
	s_cselect_b32 s25, s26, s30
	s_cselect_b32 s54, s29, s35
	s_cselect_b32 s55, s28, s34
	s_add_u32 s30, s30, 0x10080
	s_addc_u32 s31, s31, 0
	s_add_u32 s34, s34, 0x100
	v_mov_b32_e32 v2, 0
	s_addc_u32 s35, s35, 0
	s_mov_b32 s0, 0
	v_mov_b32_e32 v3, v2
	v_mov_b32_e32 v4, v2
	v_mov_b32_e32 v5, v2
	v_mov_b32_e32 v6, v2
	v_mov_b32_e32 v7, v2
	v_mov_b32_e32 v8, v2
	v_mov_b32_e32 v9, v2
	v_mov_b32_e32 v18, v2
	v_mov_b32_e32 v19, v2
	v_mov_b32_e32 v20, v2
	v_mov_b32_e32 v21, v2
	v_mov_b32_e32 v22, v2
	v_mov_b32_e32 v23, v2
	v_mov_b32_e32 v24, v2
	v_mov_b32_e32 v25, v2
	v_mov_b32_e32 v34, v2
	v_mov_b32_e32 v35, v2
	v_mov_b32_e32 v36, v2
	v_mov_b32_e32 v37, v2
	v_mov_b32_e32 v38, v2
	v_mov_b32_e32 v39, v2
	v_mov_b32_e32 v40, v2
	v_mov_b32_e32 v41, v2
	v_mov_b32_e32 v50, v2
	v_mov_b32_e32 v51, v2
	v_mov_b32_e32 v52, v2
	v_mov_b32_e32 v53, v2
	v_mov_b32_e32 v54, v2
	v_mov_b32_e32 v55, v2
	v_mov_b32_e32 v56, v2
	v_mov_b32_e32 v57, v2
	v_mov_b32_e32 v10, v2
	v_mov_b32_e32 v11, v2
	v_mov_b32_e32 v12, v2
	v_mov_b32_e32 v13, v2
	v_mov_b32_e32 v14, v2
	v_mov_b32_e32 v15, v2
	v_mov_b32_e32 v16, v2
	v_mov_b32_e32 v17, v2
	v_mov_b32_e32 v26, v2
	v_mov_b32_e32 v27, v2
	v_mov_b32_e32 v28, v2
	v_mov_b32_e32 v29, v2
	v_mov_b32_e32 v30, v2
	v_mov_b32_e32 v31, v2
	v_mov_b32_e32 v32, v2
	v_mov_b32_e32 v33, v2
	v_mov_b32_e32 v42, v2
	v_mov_b32_e32 v43, v2
	v_mov_b32_e32 v44, v2
	v_mov_b32_e32 v45, v2
	v_mov_b32_e32 v46, v2
	v_mov_b32_e32 v47, v2
	v_mov_b32_e32 v48, v2
	v_mov_b32_e32 v49, v2
	v_mov_b32_e32 v58, v2
	v_mov_b32_e32 v59, v2
	v_mov_b32_e32 v60, v2
	v_mov_b32_e32 v61, v2
	v_mov_b32_e32 v62, v2
	v_mov_b32_e32 v63, v2
	v_mov_b32_e32 v64, v2
	v_mov_b32_e32 v65, v2
	v_mov_b32_e32 v66, v2
	v_mov_b32_e32 v67, v2
	v_mov_b32_e32 v68, v2
	v_mov_b32_e32 v69, v2
	v_mov_b32_e32 v70, v2
	v_mov_b32_e32 v71, v2
	v_mov_b32_e32 v72, v2
	v_mov_b32_e32 v73, v2
	v_mov_b32_e32 v82, v2
	v_mov_b32_e32 v83, v2
	v_mov_b32_e32 v84, v2
	v_mov_b32_e32 v85, v2
	v_mov_b32_e32 v86, v2
	v_mov_b32_e32 v87, v2
	v_mov_b32_e32 v88, v2
	v_mov_b32_e32 v89, v2
	v_mov_b32_e32 v98, v2
	v_mov_b32_e32 v99, v2
	v_mov_b32_e32 v100, v2
	v_mov_b32_e32 v101, v2
	v_mov_b32_e32 v102, v2
	v_mov_b32_e32 v103, v2
	v_mov_b32_e32 v104, v2
	v_mov_b32_e32 v105, v2
	v_mov_b32_e32 v114, v2
	v_mov_b32_e32 v115, v2
	v_mov_b32_e32 v116, v2
	v_mov_b32_e32 v117, v2
	v_mov_b32_e32 v118, v2
	v_mov_b32_e32 v119, v2
	v_mov_b32_e32 v120, v2
	v_mov_b32_e32 v121, v2
	v_mov_b32_e32 v74, v2
	v_mov_b32_e32 v75, v2
	v_mov_b32_e32 v76, v2
	v_mov_b32_e32 v77, v2
	v_mov_b32_e32 v78, v2
	v_mov_b32_e32 v79, v2
	v_mov_b32_e32 v80, v2
	v_mov_b32_e32 v81, v2
	v_mov_b32_e32 v90, v2
	v_mov_b32_e32 v91, v2
	v_mov_b32_e32 v92, v2
	v_mov_b32_e32 v93, v2
	v_mov_b32_e32 v94, v2
	v_mov_b32_e32 v95, v2
	v_mov_b32_e32 v96, v2
	v_mov_b32_e32 v97, v2
	v_mov_b32_e32 v106, v2
	v_mov_b32_e32 v107, v2
	v_mov_b32_e32 v108, v2
	v_mov_b32_e32 v109, v2
	v_mov_b32_e32 v110, v2
	v_mov_b32_e32 v111, v2
	v_mov_b32_e32 v112, v2
	v_mov_b32_e32 v113, v2
	v_mov_b32_e32 v126, v2
	v_mov_b32_e32 v127, v2
	v_mov_b32_e32 v128, v2
	v_mov_b32_e32 v129, v2
	v_mov_b32_e32 v122, v2
	v_mov_b32_e32 v123, v2
	v_mov_b32_e32 v124, v2
	v_mov_b32_e32 v125, v2
	s_waitcnt vmcnt(0)

.LBB0_1260:
	s_ashr_i32 s21, s20, 31
	s_lshl_b64 s[22:23], s[20:21], 20
	s_add_u32 s22, s34, s22
	s_addc_u32 s23, s35, s23
	s_and_b64 s[24:25], s[6:7], exec
	s_cselect_b32 s21, s23, s3
	s_cselect_b32 s47, s22, s2
	s_ashr_i32 s19, s18, 31
	s_lshl_b64 s[24:25], s[18:19], 20
	s_add_u32 s24, s30, s24
	s_addc_u32 s25, s31, s25
	s_and_b64 s[28:29], s[6:7], exec
	s_cselect_b32 s19, s25, s1
	s_cselect_b32 s48, s24, s0
	s_add_u32 s28, s2, 0x80080
	s_addc_u32 s29, s3, 0
	s_add_u32 s49, s0, 0x100
	v_mov_b32_e32 v2, 0
	s_addc_u32 s50, s1, 0
	s_mov_b32 s51, -2
	v_mov_b32_e32 v3, v2
	v_mov_b32_e32 v4, v2
	v_mov_b32_e32 v5, v2
	v_mov_b32_e32 v6, v2
	v_mov_b32_e32 v7, v2
	v_mov_b32_e32 v8, v2
	v_mov_b32_e32 v9, v2
	v_mov_b32_e32 v18, v2
	v_mov_b32_e32 v19, v2
	v_mov_b32_e32 v20, v2
	v_mov_b32_e32 v21, v2
	s_waitcnt vmcnt(0)
	v_mov_b32_e32 v22, v2
	v_mov_b32_e32 v23, v2
	v_mov_b32_e32 v24, v2
	v_mov_b32_e32 v25, v2
	v_mov_b32_e32 v34, v2
	v_mov_b32_e32 v35, v2
	v_mov_b32_e32 v36, v2
	v_mov_b32_e32 v37, v2
	v_mov_b32_e32 v38, v2
	v_mov_b32_e32 v39, v2
	v_mov_b32_e32 v40, v2
	v_mov_b32_e32 v41, v2
	v_mov_b32_e32 v50, v2
	v_mov_b32_e32 v51, v2
	v_mov_b32_e32 v52, v2
	v_mov_b32_e32 v53, v2
	v_mov_b32_e32 v54, v2
	v_mov_b32_e32 v55, v2
	v_mov_b32_e32 v56, v2
	v_mov_b32_e32 v57, v2
	v_mov_b32_e32 v10, v2
	v_mov_b32_e32 v11, v2
	v_mov_b32_e32 v12, v2
	v_mov_b32_e32 v13, v2
	v_mov_b32_e32 v14, v2
	v_mov_b32_e32 v15, v2
	v_mov_b32_e32 v16, v2
	v_mov_b32_e32 v17, v2
	v_mov_b32_e32 v26, v2
	v_mov_b32_e32 v27, v2
	v_mov_b32_e32 v28, v2
	v_mov_b32_e32 v29, v2
	v_mov_b32_e32 v30, v2
	v_mov_b32_e32 v31, v2
	v_mov_b32_e32 v32, v2
	v_mov_b32_e32 v33, v2
	v_mov_b32_e32 v42, v2
	v_mov_b32_e32 v43, v2
	v_mov_b32_e32 v44, v2
	v_mov_b32_e32 v45, v2
	v_mov_b32_e32 v46, v2
	v_mov_b32_e32 v47, v2
	v_mov_b32_e32 v48, v2
	v_mov_b32_e32 v49, v2
	v_mov_b32_e32 v58, v2
	v_mov_b32_e32 v59, v2
	v_mov_b32_e32 v60, v2
	v_mov_b32_e32 v61, v2
	v_mov_b32_e32 v62, v2
	v_mov_b32_e32 v63, v2
	v_mov_b32_e32 v64, v2
	v_mov_b32_e32 v65, v2
	v_mov_b32_e32 v66, v2
	v_mov_b32_e32 v67, v2
	v_mov_b32_e32 v68, v2
	v_mov_b32_e32 v69, v2
	v_mov_b32_e32 v70, v2
	v_mov_b32_e32 v71, v2
	v_mov_b32_e32 v72, v2
	v_mov_b32_e32 v73, v2
	v_mov_b32_e32 v74, v2
	v_mov_b32_e32 v75, v2
	v_mov_b32_e32 v76, v2
	v_mov_b32_e32 v77, v2
	v_mov_b32_e32 v82, v2
	v_mov_b32_e32 v83, v2
	v_mov_b32_e32 v84, v2
	v_mov_b32_e32 v85, v2
	v_mov_b32_e32 v90, v2
	v_mov_b32_e32 v91, v2
	v_mov_b32_e32 v92, v2
	v_mov_b32_e32 v93, v2
	v_mov_b32_e32 v98, v2
	v_mov_b32_e32 v99, v2
	v_mov_b32_e32 v100, v2
	v_mov_b32_e32 v101, v2
	v_mov_b32_e32 v106, v2
	v_mov_b32_e32 v107, v2
	v_mov_b32_e32 v108, v2
	v_mov_b32_e32 v109, v2
	v_mov_b32_e32 v114, v2
	v_mov_b32_e32 v115, v2
	v_mov_b32_e32 v116, v2
	v_mov_b32_e32 v117, v2
	v_mov_b32_e32 v78, v2
	v_mov_b32_e32 v79, v2
	v_mov_b32_e32 v80, v2
	v_mov_b32_e32 v81, v2
	v_mov_b32_e32 v86, v2
	v_mov_b32_e32 v87, v2
	v_mov_b32_e32 v88, v2
	v_mov_b32_e32 v89, v2
	v_mov_b32_e32 v94, v2
	v_mov_b32_e32 v95, v2
	v_mov_b32_e32 v96, v2
	v_mov_b32_e32 v97, v2
	v_mov_b32_e32 v102, v2
	v_mov_b32_e32 v103, v2
	v_mov_b32_e32 v104, v2
	v_mov_b32_e32 v105, v2
	v_mov_b32_e32 v110, v2
	v_mov_b32_e32 v111, v2
	v_mov_b32_e32 v112, v2
	v_mov_b32_e32 v113, v2
	v_mov_b32_e32 v118, v2
	v_mov_b32_e32 v119, v2
	v_mov_b32_e32 v120, v2
	v_mov_b32_e32 v121, v2
	v_mov_b32_e32 v122, v2
	v_mov_b32_e32 v123, v2
	v_mov_b32_e32 v124, v2
	v_mov_b32_e32 v125, v2
	v_mov_b32_e32 v126, v2
	v_mov_b32_e32 v127, v2
	v_mov_b32_e32 v128, v2
	v_mov_b32_e32 v129, v2
	s_waitcnt vmcnt(0)

.LBB0_1345:
	s_ashr_i32 s25, s24, 31
	s_lshl_b64 s[26:27], s[24:25], 20
	s_add_u32 s26, s10, s26
	s_addc_u32 s27, s11, s27
	s_and_b64 s[28:29], s[6:7], exec
	s_cselect_b32 s25, s27, s3
	s_cselect_b32 s47, s26, s2
	s_ashr_i32 s23, s22, 31
	s_lshl_b64 s[28:29], s[22:23], 20
	s_add_u32 s28, s34, s28
	s_addc_u32 s29, s35, s29
	s_and_b64 s[30:31], s[6:7], exec
	s_cselect_b32 s23, s29, s1
	s_cselect_b32 s48, s28, s0
	s_add_u32 s30, s2, 0x80080
	s_addc_u32 s31, s3, 0
	s_add_u32 s49, s0, 0x100
	v_mov_b32_e32 v2, 0
	s_addc_u32 s50, s1, 0
	s_mov_b32 s51, -2
	v_mov_b32_e32 v3, v2
	v_mov_b32_e32 v4, v2
	v_mov_b32_e32 v5, v2
	v_mov_b32_e32 v6, v2
	v_mov_b32_e32 v7, v2
	v_mov_b32_e32 v8, v2
	v_mov_b32_e32 v9, v2
	v_mov_b32_e32 v18, v2
	v_mov_b32_e32 v19, v2
	v_mov_b32_e32 v20, v2
	v_mov_b32_e32 v21, v2
	s_waitcnt vmcnt(0)
	v_mov_b32_e32 v22, v2
	v_mov_b32_e32 v23, v2
	v_mov_b32_e32 v24, v2
	v_mov_b32_e32 v25, v2
	v_mov_b32_e32 v34, v2
	v_mov_b32_e32 v35, v2
	v_mov_b32_e32 v36, v2
	v_mov_b32_e32 v37, v2
	v_mov_b32_e32 v38, v2
	v_mov_b32_e32 v39, v2
	v_mov_b32_e32 v40, v2
	v_mov_b32_e32 v41, v2
	v_mov_b32_e32 v50, v2
	v_mov_b32_e32 v51, v2
	v_mov_b32_e32 v52, v2
	v_mov_b32_e32 v53, v2
	v_mov_b32_e32 v54, v2
	v_mov_b32_e32 v55, v2
	v_mov_b32_e32 v56, v2
	v_mov_b32_e32 v57, v2
	v_mov_b32_e32 v10, v2
	v_mov_b32_e32 v11, v2
	v_mov_b32_e32 v12, v2
	v_mov_b32_e32 v13, v2
	v_mov_b32_e32 v14, v2
	v_mov_b32_e32 v15, v2
	v_mov_b32_e32 v16, v2
	v_mov_b32_e32 v17, v2
	v_mov_b32_e32 v26, v2
	v_mov_b32_e32 v27, v2
	v_mov_b32_e32 v28, v2
	v_mov_b32_e32 v29, v2
	v_mov_b32_e32 v30, v2
	v_mov_b32_e32 v31, v2
	v_mov_b32_e32 v32, v2
	v_mov_b32_e32 v33, v2
	v_mov_b32_e32 v42, v2
	v_mov_b32_e32 v43, v2
	v_mov_b32_e32 v44, v2
	v_mov_b32_e32 v45, v2
	v_mov_b32_e32 v46, v2
	v_mov_b32_e32 v47, v2
	v_mov_b32_e32 v48, v2
	v_mov_b32_e32 v49, v2
	v_mov_b32_e32 v58, v2
	v_mov_b32_e32 v59, v2
	v_mov_b32_e32 v60, v2
	v_mov_b32_e32 v61, v2
	v_mov_b32_e32 v62, v2
	v_mov_b32_e32 v63, v2
	v_mov_b32_e32 v64, v2
	v_mov_b32_e32 v65, v2
	v_mov_b32_e32 v66, v2
	v_mov_b32_e32 v67, v2
	v_mov_b32_e32 v68, v2
	v_mov_b32_e32 v69, v2
	v_mov_b32_e32 v70, v2
	v_mov_b32_e32 v71, v2
	v_mov_b32_e32 v72, v2
	v_mov_b32_e32 v73, v2
	v_mov_b32_e32 v82, v2
	v_mov_b32_e32 v83, v2
	v_mov_b32_e32 v84, v2
	v_mov_b32_e32 v85, v2
	v_mov_b32_e32 v86, v2
	v_mov_b32_e32 v87, v2
	v_mov_b32_e32 v88, v2
	v_mov_b32_e32 v89, v2
	v_mov_b32_e32 v98, v2
	v_mov_b32_e32 v99, v2
	v_mov_b32_e32 v100, v2
	v_mov_b32_e32 v101, v2
	v_mov_b32_e32 v102, v2
	v_mov_b32_e32 v103, v2
	v_mov_b32_e32 v104, v2
	v_mov_b32_e32 v105, v2
	v_mov_b32_e32 v114, v2
	v_mov_b32_e32 v115, v2
	v_mov_b32_e32 v116, v2
	v_mov_b32_e32 v117, v2
	v_mov_b32_e32 v118, v2
	v_mov_b32_e32 v119, v2
	v_mov_b32_e32 v120, v2
	v_mov_b32_e32 v121, v2
	v_mov_b32_e32 v74, v2
	v_mov_b32_e32 v75, v2
	v_mov_b32_e32 v76, v2
	v_mov_b32_e32 v77, v2
	v_mov_b32_e32 v78, v2
	v_mov_b32_e32 v79, v2
	v_mov_b32_e32 v80, v2
	v_mov_b32_e32 v81, v2
	v_mov_b32_e32 v90, v2
	v_mov_b32_e32 v91, v2
	v_mov_b32_e32 v92, v2
	v_mov_b32_e32 v93, v2
	v_mov_b32_e32 v94, v2
	v_mov_b32_e32 v95, v2
	v_mov_b32_e32 v96, v2
	v_mov_b32_e32 v97, v2
	v_mov_b32_e32 v106, v2
	v_mov_b32_e32 v107, v2
	v_mov_b32_e32 v108, v2
	v_mov_b32_e32 v109, v2
	v_mov_b32_e32 v110, v2
	v_mov_b32_e32 v111, v2
	v_mov_b32_e32 v112, v2
	v_mov_b32_e32 v113, v2
	v_mov_b32_e32 v122, v2
	v_mov_b32_e32 v123, v2
	v_mov_b32_e32 v124, v2
	v_mov_b32_e32 v125, v2
	v_mov_b32_e32 v126, v2
	v_mov_b32_e32 v127, v2
	v_mov_b32_e32 v128, v2
	v_mov_b32_e32 v129, v2
	s_waitcnt vmcnt(0)
